# attention softmax math in packed f32 (v_pk_fma/v_pk_mul/v_pk_add on the contiguous score registers, exp in place)
# baseline (speedup 1.0000x reference)
.LBB0_778:
	s_add_i32 s22, s13, -1
	s_cmp_lt_u32 s22, s49
	s_cbranch_scc0 .Lattn_last
	ds_read_b128 v[228:231], v150 offset:0
	ds_read_b128 v[232:235], v150 offset:32
	ds_read_b128 v[236:239], v150 offset:64
	ds_read_b128 v[240:243], v150 offset:96
	ds_read_b128 v[244:247], v150 offset:128
	v_lshl_add_u64 v[142:143], s[92:93], 0, v[132:133]
	v_lshl_add_u64 v[140:141], s[92:93], 0, v[134:135]
	v_lshl_add_u64 v[138:139], s[92:93], 0, v[136:137]
	v_add_co_u32_e32 v34, vcc, 0x883e000, v142
	s_nop 1
	v_addc_co_u32_e32 v35, vcc, 0, v143, vcc
	global_load_dwordx4 v[66:69], v[34:35], off
	global_load_dwordx4 v[70:73], v[34:35], off offset:128
	v_add_co_u32_e32 v34, vcc, 0x883e000, v140
	s_nop 1
	v_addc_co_u32_e32 v35, vcc, 0, v141, vcc
	global_load_dwordx4 v[74:77], v[34:35], off
	global_load_dwordx4 v[78:81], v[34:35], off offset:128
	v_add_co_u32_e32 v34, vcc, 0x9a00000, v138
	s_nop 1
	v_addc_co_u32_e32 v35, vcc, 0, v139, vcc
	global_load_dwordx4 v[110:113], v[34:35], off
	s_waitcnt vmcnt(10)
	s_waitcnt lgkmcnt(4)
	v_mfma_f32_32x32x16_bf16 v[50:65], v[228:231], v[82:85], 0
	ds_read_b128 v[228:231], v150 offset:160
	s_waitcnt lgkmcnt(4)
	v_mfma_f32_32x32x16_bf16 v[50:65], v[232:235], v[86:89], v[50:65]
	ds_read_b128 v[232:235], v150 offset:6656
	s_waitcnt lgkmcnt(4)
	v_mfma_f32_32x32x16_bf16 v[50:65], v[236:239], v[90:93], v[50:65]
	ds_read_b128 v[236:239], v150 offset:6688
	s_waitcnt lgkmcnt(4)
	v_mfma_f32_32x32x16_bf16 v[50:65], v[240:243], v[94:97], v[50:65]
	ds_read_b128 v[240:243], v150 offset:6720
	s_waitcnt lgkmcnt(4)
	v_mfma_f32_32x32x16_bf16 v[50:65], v[244:247], v[98:101], v[50:65]
	ds_read_b128 v[244:247], v150 offset:6752
	s_waitcnt lgkmcnt(4)
	v_mfma_f32_32x32x16_bf16 v[50:65], v[228:231], v[102:105], v[50:65]
	ds_read_b128 v[228:231], v150 offset:6784
	s_waitcnt lgkmcnt(4)
	v_mfma_f32_32x32x16_bf16 v[34:49], v[232:235], v[82:85], 0
	ds_read_b128 v[232:235], v150 offset:6816
	s_waitcnt vmcnt(5)
	ds_write_b128 v145, v[106:109] offset:25600
	s_waitcnt lgkmcnt(5)
	v_mfma_f32_32x32x16_bf16 v[34:49], v[236:239], v[86:89], v[34:49]
	ds_read_b64_tr_b16 v[236:237], v148 offset:13312
	ds_read_b64_tr_b16 v[238:239], v148 offset:14848
	ds_write_b128 v146, v[114:117] offset:38912
	s_waitcnt lgkmcnt(7)
	v_mfma_f32_32x32x16_bf16 v[34:49], v[240:243], v[90:93], v[34:49]
	ds_read_b64_tr_b16 v[240:241], v148 offset:13376
	ds_read_b64_tr_b16 v[242:243], v148 offset:14912
	ds_write_b128 v147, v[118:121] offset:25600
	s_waitcnt lgkmcnt(9)
	v_mfma_f32_32x32x16_bf16 v[34:49], v[244:247], v[94:97], v[34:49]
	ds_read_b64_tr_b16 v[244:245], v148 offset:16384
	ds_read_b64_tr_b16 v[246:247], v148 offset:17920
	ds_write_b128 v146, v[122:125] offset:45056
	s_waitcnt lgkmcnt(11)
	v_mfma_f32_32x32x16_bf16 v[34:49], v[228:231], v[98:101], v[34:49]
	ds_read_b64_tr_b16 v[228:229], v148 offset:16448
	ds_read_b64_tr_b16 v[230:231], v148 offset:17984
	ds_write_b128 v149, v[126:129] offset:25728
	s_waitcnt lgkmcnt(13)
	v_mfma_f32_32x32x16_bf16 v[34:49], v[232:235], v[102:105], v[34:49]
	ds_read_b64_tr_b16 v[232:233], v148 offset:19456
	ds_read_b64_tr_b16 v[234:235], v148 offset:20992
	v_max3_f32 v224, s23, v50, v51
	v_max3_f32 v224, v224, v52, v53
	v_max3_f32 v224, v224, v54, v55
	v_max3_f32 v224, v224, v56, v57
	v_max3_f32 v224, v224, v58, v59
	v_max3_f32 v224, v224, v60, v61
	v_max3_f32 v224, v224, v62, v63
	v_max3_f32 v224, v224, v64, v65
	s_nop 1
	v_max3_f32 v225, s23, v34, v35
	v_max3_f32 v225, v225, v36, v37
	v_max3_f32 v225, v225, v38, v39
	v_max3_f32 v225, v225, v40, v41
	v_max3_f32 v225, v225, v42, v43
	v_max3_f32 v225, v225, v44, v45
	v_max3_f32 v225, v225, v46, v47
	v_max3_f32 v225, v225, v48, v49
	v_max_f32_e32 v224, v224, v225
	v_mov_b32_e32 v225, v224
	s_nop 1
	v_permlane32_swap_b32_e32 v224, v225
	v_max_f32_e32 v224, v224, v225
	v_mul_f32_e32 v224, s55, v224
	v_max_f32_e32 v214, v213, v224
	v_sub_f32_e32 v226, v213, v214
	v_exp_f32_e32 v226, v226
	v_mov_b32_e32 v224, v214
	v_pk_fma_f32 v[50:51], v[50:51], s[54:55], v[224:225] op_sel:[0,1,0] op_sel_hi:[1,1,0] neg_lo:[0,0,1] neg_hi:[0,0,1]
	v_pk_fma_f32 v[52:53], v[52:53], s[54:55], v[224:225] op_sel:[0,1,0] op_sel_hi:[1,1,0] neg_lo:[0,0,1] neg_hi:[0,0,1]
	v_pk_fma_f32 v[54:55], v[54:55], s[54:55], v[224:225] op_sel:[0,1,0] op_sel_hi:[1,1,0] neg_lo:[0,0,1] neg_hi:[0,0,1]
	v_pk_fma_f32 v[56:57], v[56:57], s[54:55], v[224:225] op_sel:[0,1,0] op_sel_hi:[1,1,0] neg_lo:[0,0,1] neg_hi:[0,0,1]
	v_exp_f32_e32 v50, v50
	v_exp_f32_e32 v51, v51
	v_exp_f32_e32 v52, v52
	v_exp_f32_e32 v53, v53
	v_exp_f32_e32 v54, v54
	v_exp_f32_e32 v55, v55
	v_exp_f32_e32 v56, v56
	v_exp_f32_e32 v57, v57
	v_mul_f32_e32 v154, v154, v226
	v_pk_mul_f32 v[18:19], v[18:19], v[226:227] op_sel_hi:[1,0]
	v_pk_mul_f32 v[20:21], v[20:21], v[226:227] op_sel_hi:[1,0]
	v_pk_mul_f32 v[22:23], v[22:23], v[226:227] op_sel_hi:[1,0]
	v_pk_mul_f32 v[24:25], v[24:25], v[226:227] op_sel_hi:[1,0]
	v_pk_mul_f32 v[26:27], v[26:27], v[226:227] op_sel_hi:[1,0]
	v_pk_mul_f32 v[28:29], v[28:29], v[226:227] op_sel_hi:[1,0]
	v_pk_mul_f32 v[30:31], v[30:31], v[226:227] op_sel_hi:[1,0]
	v_pk_mul_f32 v[32:33], v[32:33], v[226:227] op_sel_hi:[1,0]
	v_pk_mul_f32 v[2:3], v[2:3], v[226:227] op_sel_hi:[1,0]
	v_pk_mul_f32 v[4:5], v[4:5], v[226:227] op_sel_hi:[1,0]
	v_pk_mul_f32 v[6:7], v[6:7], v[226:227] op_sel_hi:[1,0]
	v_pk_mul_f32 v[8:9], v[8:9], v[226:227] op_sel_hi:[1,0]
	v_pk_mul_f32 v[10:11], v[10:11], v[226:227] op_sel_hi:[1,0]
	v_pk_mul_f32 v[12:13], v[12:13], v[226:227] op_sel_hi:[1,0]
	v_pk_mul_f32 v[14:15], v[14:15], v[226:227] op_sel_hi:[1,0]
	v_pk_mul_f32 v[16:17], v[16:17], v[226:227] op_sel_hi:[1,0]
	v_cvt_pk_bf16_f32 v216, v50, v51
	v_cvt_pk_bf16_f32 v217, v52, v53
	v_cvt_pk_bf16_f32 v218, v54, v55
	v_cvt_pk_bf16_f32 v219, v56, v57
	v_pk_add_f32 v[50:51], v[50:51], v[52:53]
	v_pk_add_f32 v[54:55], v[54:55], v[56:57]
	v_pk_add_f32 v[50:51], v[50:51], v[54:55]
	v_add_f32_e32 v50, v50, v51
	s_waitcnt lgkmcnt(12)
	v_mfma_f32_32x32x16_bf16 v[18:33], v[236:239], v[216:219], v[18:33]
	ds_read_b64_tr_b16 v[236:237], v148 offset:19520
	ds_read_b64_tr_b16 v[238:239], v148 offset:21056
	s_waitcnt lgkmcnt(11)
	v_mfma_f32_32x32x16_bf16 v[2:17], v[240:243], v[216:219], v[2:17]
	ds_read_b64_tr_b16 v[240:241], v148 offset:22528
	ds_read_b64_tr_b16 v[242:243], v148 offset:24064
	v_pk_fma_f32 v[58:59], v[58:59], s[54:55], v[224:225] op_sel:[0,1,0] op_sel_hi:[1,1,0] neg_lo:[0,0,1] neg_hi:[0,0,1]
	v_pk_fma_f32 v[60:61], v[60:61], s[54:55], v[224:225] op_sel:[0,1,0] op_sel_hi:[1,1,0] neg_lo:[0,0,1] neg_hi:[0,0,1]
	v_pk_fma_f32 v[62:63], v[62:63], s[54:55], v[224:225] op_sel:[0,1,0] op_sel_hi:[1,1,0] neg_lo:[0,0,1] neg_hi:[0,0,1]
	v_pk_fma_f32 v[64:65], v[64:65], s[54:55], v[224:225] op_sel:[0,1,0] op_sel_hi:[1,1,0] neg_lo:[0,0,1] neg_hi:[0,0,1]
	v_exp_f32_e32 v58, v58
	v_exp_f32_e32 v59, v59
	v_exp_f32_e32 v60, v60
	v_exp_f32_e32 v61, v61
	v_exp_f32_e32 v62, v62
	v_exp_f32_e32 v63, v63
	v_exp_f32_e32 v64, v64
	v_exp_f32_e32 v65, v65
	v_cvt_pk_bf16_f32 v220, v58, v59
	v_cvt_pk_bf16_f32 v221, v60, v61
	v_cvt_pk_bf16_f32 v222, v62, v63
	v_cvt_pk_bf16_f32 v223, v64, v65
	v_pk_add_f32 v[58:59], v[58:59], v[60:61]
	v_pk_add_f32 v[62:63], v[62:63], v[64:65]
	v_pk_add_f32 v[58:59], v[58:59], v[62:63]
	v_add_f32_e32 v58, v58, v59
	s_waitcnt lgkmcnt(10)
	v_mfma_f32_32x32x16_bf16 v[18:33], v[244:247], v[220:223], v[18:33]
	ds_read_b64_tr_b16 v[244:245], v148 offset:22592
	ds_read_b64_tr_b16 v[246:247], v148 offset:24128
	s_waitcnt lgkmcnt(9)
	v_mfma_f32_32x32x16_bf16 v[2:17], v[228:231], v[220:223], v[2:17]
	v_pk_fma_f32 v[34:35], v[34:35], s[54:55], v[224:225] op_sel:[0,1,0] op_sel_hi:[1,1,0] neg_lo:[0,0,1] neg_hi:[0,0,1]
	v_pk_fma_f32 v[36:37], v[36:37], s[54:55], v[224:225] op_sel:[0,1,0] op_sel_hi:[1,1,0] neg_lo:[0,0,1] neg_hi:[0,0,1]
	v_pk_fma_f32 v[38:39], v[38:39], s[54:55], v[224:225] op_sel:[0,1,0] op_sel_hi:[1,1,0] neg_lo:[0,0,1] neg_hi:[0,0,1]
	v_pk_fma_f32 v[40:41], v[40:41], s[54:55], v[224:225] op_sel:[0,1,0] op_sel_hi:[1,1,0] neg_lo:[0,0,1] neg_hi:[0,0,1]
	v_exp_f32_e32 v34, v34
	v_exp_f32_e32 v35, v35
	v_exp_f32_e32 v36, v36
	v_exp_f32_e32 v37, v37
	v_exp_f32_e32 v38, v38
	v_exp_f32_e32 v39, v39
	v_exp_f32_e32 v40, v40
	v_exp_f32_e32 v41, v41
	v_cvt_pk_bf16_f32 v216, v34, v35
	v_cvt_pk_bf16_f32 v217, v36, v37
	v_cvt_pk_bf16_f32 v218, v38, v39
	v_cvt_pk_bf16_f32 v219, v40, v41
	v_pk_add_f32 v[34:35], v[34:35], v[36:37]
	v_pk_add_f32 v[38:39], v[38:39], v[40:41]
	v_pk_add_f32 v[34:35], v[34:35], v[38:39]
	v_add_f32_e32 v34, v34, v35
	s_waitcnt lgkmcnt(6)
	v_mfma_f32_32x32x16_bf16 v[18:33], v[232:235], v[216:219], v[18:33]
	s_waitcnt lgkmcnt(4)
	v_mfma_f32_32x32x16_bf16 v[2:17], v[236:239], v[216:219], v[2:17]
	v_pk_fma_f32 v[42:43], v[42:43], s[54:55], v[224:225] op_sel:[0,1,0] op_sel_hi:[1,1,0] neg_lo:[0,0,1] neg_hi:[0,0,1]
	v_pk_fma_f32 v[44:45], v[44:45], s[54:55], v[224:225] op_sel:[0,1,0] op_sel_hi:[1,1,0] neg_lo:[0,0,1] neg_hi:[0,0,1]
	v_pk_fma_f32 v[46:47], v[46:47], s[54:55], v[224:225] op_sel:[0,1,0] op_sel_hi:[1,1,0] neg_lo:[0,0,1] neg_hi:[0,0,1]
	v_pk_fma_f32 v[48:49], v[48:49], s[54:55], v[224:225] op_sel:[0,1,0] op_sel_hi:[1,1,0] neg_lo:[0,0,1] neg_hi:[0,0,1]
	v_exp_f32_e32 v42, v42
	v_exp_f32_e32 v43, v43
	v_exp_f32_e32 v44, v44
	v_exp_f32_e32 v45, v45
	v_exp_f32_e32 v46, v46
	v_exp_f32_e32 v47, v47
	v_exp_f32_e32 v48, v48
	v_exp_f32_e32 v49, v49
	v_cvt_pk_bf16_f32 v220, v42, v43
	v_cvt_pk_bf16_f32 v221, v44, v45
	v_cvt_pk_bf16_f32 v222, v46, v47
	v_cvt_pk_bf16_f32 v223, v48, v49
	v_pk_add_f32 v[42:43], v[42:43], v[44:45]
	v_pk_add_f32 v[46:47], v[46:47], v[48:49]
	v_pk_add_f32 v[42:43], v[42:43], v[46:47]
	v_add_f32_e32 v42, v42, v43
	s_waitcnt lgkmcnt(2)
	v_mfma_f32_32x32x16_bf16 v[18:33], v[240:243], v[220:223], v[18:33]
	s_waitcnt lgkmcnt(0)
	v_mfma_f32_32x32x16_bf16 v[2:17], v[244:247], v[220:223], v[2:17]
	v_add_f32_e32 v50, v50, v58
	v_add_f32_e32 v34, v34, v42
	v_add_f32_e32 v50, v50, v34
	v_add_f32_e32 v154, v154, v50
	s_waitcnt lgkmcnt(0)
	s_barrier
	ds_read_b128 v[228:231], v150 offset:25600
	ds_read_b128 v[232:235], v150 offset:25632
	ds_read_b128 v[236:239], v150 offset:25664
	ds_read_b128 v[240:243], v150 offset:25696
	ds_read_b128 v[244:247], v150 offset:25728
	v_lshl_add_u64 v[142:143], s[92:93], 0, v[132:133]
	v_lshl_add_u64 v[140:141], s[92:93], 0, v[134:135]
	v_lshl_add_u64 v[138:139], s[92:93], 0, v[136:137]
	v_add_co_u32_e32 v34, vcc, 0x885e000, v142
	s_nop 1
	v_addc_co_u32_e32 v35, vcc, 0, v143, vcc
	global_load_dwordx4 v[106:109], v[34:35], off
	global_load_dwordx4 v[114:117], v[34:35], off offset:128
	v_add_co_u32_e32 v34, vcc, 0x885e000, v140
	s_nop 1
	v_addc_co_u32_e32 v35, vcc, 0, v141, vcc
	global_load_dwordx4 v[118:121], v[34:35], off
	global_load_dwordx4 v[122:125], v[34:35], off offset:128
	v_add_co_u32_e32 v34, vcc, 0x9a01000, v138
	s_nop 1
	v_addc_co_u32_e32 v35, vcc, 0, v139, vcc
	global_load_dwordx4 v[126:129], v[34:35], off
	s_waitcnt lgkmcnt(4)
	v_mfma_f32_32x32x16_bf16 v[50:65], v[228:231], v[82:85], 0
	ds_read_b128 v[228:231], v150 offset:25760
	s_waitcnt lgkmcnt(4)
	v_mfma_f32_32x32x16_bf16 v[50:65], v[232:235], v[86:89], v[50:65]
	ds_read_b128 v[232:235], v150 offset:32256
	s_waitcnt lgkmcnt(4)
	v_mfma_f32_32x32x16_bf16 v[50:65], v[236:239], v[90:93], v[50:65]
	ds_read_b128 v[236:239], v150 offset:32288
	s_waitcnt lgkmcnt(4)
	v_mfma_f32_32x32x16_bf16 v[50:65], v[240:243], v[94:97], v[50:65]
	ds_read_b128 v[240:243], v150 offset:32320
	s_waitcnt lgkmcnt(4)
	v_mfma_f32_32x32x16_bf16 v[50:65], v[244:247], v[98:101], v[50:65]
	ds_read_b128 v[244:247], v150 offset:32352
	s_waitcnt lgkmcnt(4)
	v_mfma_f32_32x32x16_bf16 v[50:65], v[228:231], v[102:105], v[50:65]
	ds_read_b128 v[228:231], v150 offset:32384
	s_waitcnt lgkmcnt(4)
	v_mfma_f32_32x32x16_bf16 v[34:49], v[232:235], v[82:85], 0
	ds_read_b128 v[232:235], v150 offset:32416
	s_waitcnt vmcnt(5)
	ds_write_b128 v145, v[66:69] offset:0
	s_waitcnt lgkmcnt(5)
	v_mfma_f32_32x32x16_bf16 v[34:49], v[236:239], v[86:89], v[34:49]
	ds_read_b64_tr_b16 v[236:237], v148 offset:38912
	ds_read_b64_tr_b16 v[238:239], v148 offset:40448
	ds_write_b128 v146, v[70:73] offset:13312
	s_waitcnt lgkmcnt(7)
	v_mfma_f32_32x32x16_bf16 v[34:49], v[240:243], v[90:93], v[34:49]
	ds_read_b64_tr_b16 v[240:241], v148 offset:38976
	ds_read_b64_tr_b16 v[242:243], v148 offset:40512
	ds_write_b128 v147, v[74:77] offset:0
	s_waitcnt lgkmcnt(9)
	v_mfma_f32_32x32x16_bf16 v[34:49], v[244:247], v[94:97], v[34:49]
	ds_read_b64_tr_b16 v[244:245], v148 offset:41984
	ds_read_b64_tr_b16 v[246:247], v148 offset:43520
	ds_write_b128 v146, v[78:81] offset:19456
	s_waitcnt lgkmcnt(11)
	v_mfma_f32_32x32x16_bf16 v[34:49], v[228:231], v[98:101], v[34:49]
	ds_read_b64_tr_b16 v[228:229], v148 offset:42048
	ds_read_b64_tr_b16 v[230:231], v148 offset:43584
	ds_write_b128 v149, v[110:113] offset:128
	s_waitcnt lgkmcnt(13)
	v_mfma_f32_32x32x16_bf16 v[34:49], v[232:235], v[102:105], v[34:49]
	ds_read_b64_tr_b16 v[232:233], v148 offset:45056
	ds_read_b64_tr_b16 v[234:235], v148 offset:46592
	v_max3_f32 v224, s23, v50, v51
	v_max3_f32 v224, v224, v52, v53
	v_max3_f32 v224, v224, v54, v55
	v_max3_f32 v224, v224, v56, v57
	v_max3_f32 v224, v224, v58, v59
	v_max3_f32 v224, v224, v60, v61
	v_max3_f32 v224, v224, v62, v63
	v_max3_f32 v224, v224, v64, v65
	s_nop 1
	v_max3_f32 v225, s23, v34, v35
	v_max3_f32 v225, v225, v36, v37
	v_max3_f32 v225, v225, v38, v39
	v_max3_f32 v225, v225, v40, v41
	v_max3_f32 v225, v225, v42, v43
	v_max3_f32 v225, v225, v44, v45
	v_max3_f32 v225, v225, v46, v47
	v_max3_f32 v225, v225, v48, v49
	v_max_f32_e32 v224, v224, v225
	v_mov_b32_e32 v225, v224
	s_nop 1
	v_permlane32_swap_b32_e32 v224, v225
	v_max_f32_e32 v224, v224, v225
	v_mul_f32_e32 v224, s55, v224
	v_max_f32_e32 v213, v214, v224
	v_sub_f32_e32 v226, v214, v213
	v_exp_f32_e32 v226, v226
	v_mov_b32_e32 v224, v213
	v_pk_fma_f32 v[50:51], v[50:51], s[54:55], v[224:225] op_sel:[0,1,0] op_sel_hi:[1,1,0] neg_lo:[0,0,1] neg_hi:[0,0,1]
	v_pk_fma_f32 v[52:53], v[52:53], s[54:55], v[224:225] op_sel:[0,1,0] op_sel_hi:[1,1,0] neg_lo:[0,0,1] neg_hi:[0,0,1]
	v_pk_fma_f32 v[54:55], v[54:55], s[54:55], v[224:225] op_sel:[0,1,0] op_sel_hi:[1,1,0] neg_lo:[0,0,1] neg_hi:[0,0,1]
	v_pk_fma_f32 v[56:57], v[56:57], s[54:55], v[224:225] op_sel:[0,1,0] op_sel_hi:[1,1,0] neg_lo:[0,0,1] neg_hi:[0,0,1]
	v_exp_f32_e32 v50, v50
	v_exp_f32_e32 v51, v51
	v_exp_f32_e32 v52, v52
	v_exp_f32_e32 v53, v53
	v_exp_f32_e32 v54, v54
	v_exp_f32_e32 v55, v55
	v_exp_f32_e32 v56, v56
	v_exp_f32_e32 v57, v57
	v_mul_f32_e32 v154, v154, v226
	v_pk_mul_f32 v[18:19], v[18:19], v[226:227] op_sel_hi:[1,0]
	v_pk_mul_f32 v[20:21], v[20:21], v[226:227] op_sel_hi:[1,0]
	v_pk_mul_f32 v[22:23], v[22:23], v[226:227] op_sel_hi:[1,0]
	v_pk_mul_f32 v[24:25], v[24:25], v[226:227] op_sel_hi:[1,0]
	v_pk_mul_f32 v[26:27], v[26:27], v[226:227] op_sel_hi:[1,0]
	v_pk_mul_f32 v[28:29], v[28:29], v[226:227] op_sel_hi:[1,0]
	v_pk_mul_f32 v[30:31], v[30:31], v[226:227] op_sel_hi:[1,0]
	v_pk_mul_f32 v[32:33], v[32:33], v[226:227] op_sel_hi:[1,0]
	v_pk_mul_f32 v[2:3], v[2:3], v[226:227] op_sel_hi:[1,0]
	v_pk_mul_f32 v[4:5], v[4:5], v[226:227] op_sel_hi:[1,0]
	v_pk_mul_f32 v[6:7], v[6:7], v[226:227] op_sel_hi:[1,0]
	v_pk_mul_f32 v[8:9], v[8:9], v[226:227] op_sel_hi:[1,0]
	v_pk_mul_f32 v[10:11], v[10:11], v[226:227] op_sel_hi:[1,0]
	v_pk_mul_f32 v[12:13], v[12:13], v[226:227] op_sel_hi:[1,0]
	v_pk_mul_f32 v[14:15], v[14:15], v[226:227] op_sel_hi:[1,0]
	v_pk_mul_f32 v[16:17], v[16:17], v[226:227] op_sel_hi:[1,0]
	v_cvt_pk_bf16_f32 v216, v50, v51
	v_cvt_pk_bf16_f32 v217, v52, v53
	v_cvt_pk_bf16_f32 v218, v54, v55
	v_cvt_pk_bf16_f32 v219, v56, v57
	v_pk_add_f32 v[50:51], v[50:51], v[52:53]
	v_pk_add_f32 v[54:55], v[54:55], v[56:57]
	v_pk_add_f32 v[50:51], v[50:51], v[54:55]
	v_add_f32_e32 v50, v50, v51
	s_waitcnt lgkmcnt(12)
	v_mfma_f32_32x32x16_bf16 v[18:33], v[236:239], v[216:219], v[18:33]
	ds_read_b64_tr_b16 v[236:237], v148 offset:45120
	ds_read_b64_tr_b16 v[238:239], v148 offset:46656
	s_waitcnt lgkmcnt(11)
	v_mfma_f32_32x32x16_bf16 v[2:17], v[240:243], v[216:219], v[2:17]
	ds_read_b64_tr_b16 v[240:241], v148 offset:48128
	ds_read_b64_tr_b16 v[242:243], v148 offset:49664
	v_pk_fma_f32 v[58:59], v[58:59], s[54:55], v[224:225] op_sel:[0,1,0] op_sel_hi:[1,1,0] neg_lo:[0,0,1] neg_hi:[0,0,1]
	v_pk_fma_f32 v[60:61], v[60:61], s[54:55], v[224:225] op_sel:[0,1,0] op_sel_hi:[1,1,0] neg_lo:[0,0,1] neg_hi:[0,0,1]
	v_pk_fma_f32 v[62:63], v[62:63], s[54:55], v[224:225] op_sel:[0,1,0] op_sel_hi:[1,1,0] neg_lo:[0,0,1] neg_hi:[0,0,1]
	v_pk_fma_f32 v[64:65], v[64:65], s[54:55], v[224:225] op_sel:[0,1,0] op_sel_hi:[1,1,0] neg_lo:[0,0,1] neg_hi:[0,0,1]
	v_exp_f32_e32 v58, v58
	v_exp_f32_e32 v59, v59
	v_exp_f32_e32 v60, v60
	v_exp_f32_e32 v61, v61
	v_exp_f32_e32 v62, v62
	v_exp_f32_e32 v63, v63
	v_exp_f32_e32 v64, v64
	v_exp_f32_e32 v65, v65
	v_cvt_pk_bf16_f32 v220, v58, v59
	v_cvt_pk_bf16_f32 v221, v60, v61
	v_cvt_pk_bf16_f32 v222, v62, v63
	v_cvt_pk_bf16_f32 v223, v64, v65
	v_pk_add_f32 v[58:59], v[58:59], v[60:61]
	v_pk_add_f32 v[62:63], v[62:63], v[64:65]
	v_pk_add_f32 v[58:59], v[58:59], v[62:63]
	v_add_f32_e32 v58, v58, v59
	s_waitcnt lgkmcnt(10)
	v_mfma_f32_32x32x16_bf16 v[18:33], v[244:247], v[220:223], v[18:33]
	ds_read_b64_tr_b16 v[244:245], v148 offset:48192
	ds_read_b64_tr_b16 v[246:247], v148 offset:49728
	s_waitcnt lgkmcnt(9)
	v_mfma_f32_32x32x16_bf16 v[2:17], v[228:231], v[220:223], v[2:17]
	v_pk_fma_f32 v[34:35], v[34:35], s[54:55], v[224:225] op_sel:[0,1,0] op_sel_hi:[1,1,0] neg_lo:[0,0,1] neg_hi:[0,0,1]
	v_pk_fma_f32 v[36:37], v[36:37], s[54:55], v[224:225] op_sel:[0,1,0] op_sel_hi:[1,1,0] neg_lo:[0,0,1] neg_hi:[0,0,1]
	v_pk_fma_f32 v[38:39], v[38:39], s[54:55], v[224:225] op_sel:[0,1,0] op_sel_hi:[1,1,0] neg_lo:[0,0,1] neg_hi:[0,0,1]
	v_pk_fma_f32 v[40:41], v[40:41], s[54:55], v[224:225] op_sel:[0,1,0] op_sel_hi:[1,1,0] neg_lo:[0,0,1] neg_hi:[0,0,1]
	v_exp_f32_e32 v34, v34
	v_exp_f32_e32 v35, v35
	v_exp_f32_e32 v36, v36
	v_exp_f32_e32 v37, v37
	v_exp_f32_e32 v38, v38
	v_exp_f32_e32 v39, v39
	v_exp_f32_e32 v40, v40
	v_exp_f32_e32 v41, v41
	v_cvt_pk_bf16_f32 v216, v34, v35
	v_cvt_pk_bf16_f32 v217, v36, v37
	v_cvt_pk_bf16_f32 v218, v38, v39
	v_cvt_pk_bf16_f32 v219, v40, v41
	v_pk_add_f32 v[34:35], v[34:35], v[36:37]
	v_pk_add_f32 v[38:39], v[38:39], v[40:41]
	v_pk_add_f32 v[34:35], v[34:35], v[38:39]
	v_add_f32_e32 v34, v34, v35
	s_waitcnt lgkmcnt(6)
	v_mfma_f32_32x32x16_bf16 v[18:33], v[232:235], v[216:219], v[18:33]
	s_waitcnt lgkmcnt(4)
	v_mfma_f32_32x32x16_bf16 v[2:17], v[236:239], v[216:219], v[2:17]
	v_pk_fma_f32 v[42:43], v[42:43], s[54:55], v[224:225] op_sel:[0,1,0] op_sel_hi:[1,1,0] neg_lo:[0,0,1] neg_hi:[0,0,1]
	v_pk_fma_f32 v[44:45], v[44:45], s[54:55], v[224:225] op_sel:[0,1,0] op_sel_hi:[1,1,0] neg_lo:[0,0,1] neg_hi:[0,0,1]
	v_pk_fma_f32 v[46:47], v[46:47], s[54:55], v[224:225] op_sel:[0,1,0] op_sel_hi:[1,1,0] neg_lo:[0,0,1] neg_hi:[0,0,1]
	v_pk_fma_f32 v[48:49], v[48:49], s[54:55], v[224:225] op_sel:[0,1,0] op_sel_hi:[1,1,0] neg_lo:[0,0,1] neg_hi:[0,0,1]
	v_exp_f32_e32 v42, v42
	v_exp_f32_e32 v43, v43
	v_exp_f32_e32 v44, v44
	v_exp_f32_e32 v45, v45
	v_exp_f32_e32 v46, v46
	v_exp_f32_e32 v47, v47
	v_exp_f32_e32 v48, v48
	v_exp_f32_e32 v49, v49
	v_cvt_pk_bf16_f32 v220, v42, v43
	v_cvt_pk_bf16_f32 v221, v44, v45
	v_cvt_pk_bf16_f32 v222, v46, v47
	v_cvt_pk_bf16_f32 v223, v48, v49
	v_pk_add_f32 v[42:43], v[42:43], v[44:45]
	v_pk_add_f32 v[46:47], v[46:47], v[48:49]
	v_pk_add_f32 v[42:43], v[42:43], v[46:47]
	v_add_f32_e32 v42, v42, v43
	s_waitcnt lgkmcnt(2)
	v_mfma_f32_32x32x16_bf16 v[18:33], v[240:243], v[220:223], v[18:33]
	s_waitcnt lgkmcnt(0)
	v_mfma_f32_32x32x16_bf16 v[2:17], v[244:247], v[220:223], v[2:17]
	v_add_f32_e32 v50, v50, v58
	v_add_f32_e32 v34, v34, v42
	v_add_f32_e32 v50, v50, v34
	v_add_f32_e32 v154, v154, v50
	s_waitcnt lgkmcnt(0)
	s_barrier
	s_mov_b64 s[0:1], 0x2000
	v_lshl_add_u64 v[136:137], v[136:137], 0, s[0:1]
	s_mov_b64 s[0:1], 0x40000
	v_lshl_add_u64 v[134:135], v[134:135], 0, s[0:1]
	v_lshl_add_u64 v[132:133], v[132:133], 0, s[0:1]
	s_add_i32 s13, s13, 2
	s_branch .LBB0_778
.Lattn_last:
	ds_read_b128 v[228:231], v150 offset:0
	ds_read_b128 v[232:235], v150 offset:32
	ds_read_b128 v[236:239], v150 offset:64
	ds_read_b128 v[240:243], v150 offset:96
	ds_read_b128 v[244:247], v150 offset:128
	s_waitcnt lgkmcnt(4)
	v_mfma_f32_32x32x16_bf16 v[50:65], v[228:231], v[82:85], 0
	ds_read_b128 v[228:231], v150 offset:160
	s_waitcnt lgkmcnt(4)
	v_mfma_f32_32x32x16_bf16 v[50:65], v[232:235], v[86:89], v[50:65]
	ds_read_b128 v[232:235], v150 offset:6656
	s_waitcnt lgkmcnt(4)
	v_mfma_f32_32x32x16_bf16 v[50:65], v[236:239], v[90:93], v[50:65]
	ds_read_b128 v[236:239], v150 offset:6688
	s_waitcnt lgkmcnt(4)
	v_mfma_f32_32x32x16_bf16 v[50:65], v[240:243], v[94:97], v[50:65]
	ds_read_b128 v[240:243], v150 offset:6720
	s_waitcnt lgkmcnt(4)
	v_mfma_f32_32x32x16_bf16 v[50:65], v[244:247], v[98:101], v[50:65]
	ds_read_b128 v[244:247], v150 offset:6752
	s_waitcnt lgkmcnt(4)
	v_mfma_f32_32x32x16_bf16 v[50:65], v[228:231], v[102:105], v[50:65]
	ds_read_b128 v[228:231], v150 offset:6784
	s_waitcnt lgkmcnt(4)
	v_mfma_f32_32x32x16_bf16 v[34:49], v[232:235], v[82:85], 0
	ds_read_b128 v[232:235], v150 offset:6816
	s_waitcnt vmcnt(0)
	ds_write_b128 v145, v[106:109] offset:25600
	s_waitcnt lgkmcnt(5)
	v_mfma_f32_32x32x16_bf16 v[34:49], v[236:239], v[86:89], v[34:49]
	ds_read_b64_tr_b16 v[236:237], v148 offset:13312
	ds_read_b64_tr_b16 v[238:239], v148 offset:14848
	ds_write_b128 v146, v[114:117] offset:38912
	s_waitcnt lgkmcnt(7)
	v_mfma_f32_32x32x16_bf16 v[34:49], v[240:243], v[90:93], v[34:49]
	ds_read_b64_tr_b16 v[240:241], v148 offset:13376
	ds_read_b64_tr_b16 v[242:243], v148 offset:14912
	ds_write_b128 v147, v[118:121] offset:25600
	s_waitcnt lgkmcnt(9)
	v_mfma_f32_32x32x16_bf16 v[34:49], v[244:247], v[94:97], v[34:49]
	ds_read_b64_tr_b16 v[244:245], v148 offset:16384
	ds_read_b64_tr_b16 v[246:247], v148 offset:17920
	ds_write_b128 v146, v[122:125] offset:45056
	s_waitcnt lgkmcnt(11)
	v_mfma_f32_32x32x16_bf16 v[34:49], v[228:231], v[98:101], v[34:49]
	ds_read_b64_tr_b16 v[228:229], v148 offset:16448
	ds_read_b64_tr_b16 v[230:231], v148 offset:17984
	ds_write_b128 v149, v[126:129] offset:25728
	s_waitcnt lgkmcnt(13)
	v_mfma_f32_32x32x16_bf16 v[34:49], v[232:235], v[102:105], v[34:49]
	ds_read_b64_tr_b16 v[232:233], v148 offset:19456
	ds_read_b64_tr_b16 v[234:235], v148 offset:20992
	v_max3_f32 v224, s23, v50, v51
	v_max3_f32 v224, v224, v52, v53
	v_max3_f32 v224, v224, v54, v55
	v_max3_f32 v224, v224, v56, v57
	v_max3_f32 v224, v224, v58, v59
	v_max3_f32 v224, v224, v60, v61
	v_max3_f32 v224, v224, v62, v63
	v_max3_f32 v224, v224, v64, v65
	s_nop 1
	v_max3_f32 v225, s23, v34, v35
	v_max3_f32 v225, v225, v36, v37
	v_max3_f32 v225, v225, v38, v39
	v_max3_f32 v225, v225, v40, v41
	v_max3_f32 v225, v225, v42, v43
	v_max3_f32 v225, v225, v44, v45
	v_max3_f32 v225, v225, v46, v47
	v_max3_f32 v225, v225, v48, v49
	v_max_f32_e32 v224, v224, v225
	v_mov_b32_e32 v225, v224
	s_nop 1
	v_permlane32_swap_b32_e32 v224, v225
	v_max_f32_e32 v224, v224, v225
	v_mul_f32_e32 v224, s55, v224
	v_max_f32_e32 v214, v213, v224
	v_sub_f32_e32 v226, v213, v214
	v_exp_f32_e32 v226, v226
	v_mov_b32_e32 v224, v214
	v_pk_fma_f32 v[50:51], v[50:51], s[54:55], v[224:225] op_sel:[0,1,0] op_sel_hi:[1,1,0] neg_lo:[0,0,1] neg_hi:[0,0,1]
	v_pk_fma_f32 v[52:53], v[52:53], s[54:55], v[224:225] op_sel:[0,1,0] op_sel_hi:[1,1,0] neg_lo:[0,0,1] neg_hi:[0,0,1]
	v_pk_fma_f32 v[54:55], v[54:55], s[54:55], v[224:225] op_sel:[0,1,0] op_sel_hi:[1,1,0] neg_lo:[0,0,1] neg_hi:[0,0,1]
	v_pk_fma_f32 v[56:57], v[56:57], s[54:55], v[224:225] op_sel:[0,1,0] op_sel_hi:[1,1,0] neg_lo:[0,0,1] neg_hi:[0,0,1]
	v_exp_f32_e32 v50, v50
	v_exp_f32_e32 v51, v51
	v_exp_f32_e32 v52, v52
	v_exp_f32_e32 v53, v53
	v_exp_f32_e32 v54, v54
	v_exp_f32_e32 v55, v55
	v_exp_f32_e32 v56, v56
	v_exp_f32_e32 v57, v57
	v_mul_f32_e32 v154, v154, v226
	v_pk_mul_f32 v[18:19], v[18:19], v[226:227] op_sel_hi:[1,0]
	v_pk_mul_f32 v[20:21], v[20:21], v[226:227] op_sel_hi:[1,0]
	v_pk_mul_f32 v[22:23], v[22:23], v[226:227] op_sel_hi:[1,0]
	v_pk_mul_f32 v[24:25], v[24:25], v[226:227] op_sel_hi:[1,0]
	v_pk_mul_f32 v[26:27], v[26:27], v[226:227] op_sel_hi:[1,0]
	v_pk_mul_f32 v[28:29], v[28:29], v[226:227] op_sel_hi:[1,0]
	v_pk_mul_f32 v[30:31], v[30:31], v[226:227] op_sel_hi:[1,0]
	v_pk_mul_f32 v[32:33], v[32:33], v[226:227] op_sel_hi:[1,0]
	v_pk_mul_f32 v[2:3], v[2:3], v[226:227] op_sel_hi:[1,0]
	v_pk_mul_f32 v[4:5], v[4:5], v[226:227] op_sel_hi:[1,0]
	v_pk_mul_f32 v[6:7], v[6:7], v[226:227] op_sel_hi:[1,0]
	v_pk_mul_f32 v[8:9], v[8:9], v[226:227] op_sel_hi:[1,0]
	v_pk_mul_f32 v[10:11], v[10:11], v[226:227] op_sel_hi:[1,0]
	v_pk_mul_f32 v[12:13], v[12:13], v[226:227] op_sel_hi:[1,0]
	v_pk_mul_f32 v[14:15], v[14:15], v[226:227] op_sel_hi:[1,0]
	v_pk_mul_f32 v[16:17], v[16:17], v[226:227] op_sel_hi:[1,0]
	v_cvt_pk_bf16_f32 v216, v50, v51
	v_cvt_pk_bf16_f32 v217, v52, v53
	v_cvt_pk_bf16_f32 v218, v54, v55
	v_cvt_pk_bf16_f32 v219, v56, v57
	v_pk_add_f32 v[50:51], v[50:51], v[52:53]
	v_pk_add_f32 v[54:55], v[54:55], v[56:57]
	v_pk_add_f32 v[50:51], v[50:51], v[54:55]
	v_add_f32_e32 v50, v50, v51
	s_waitcnt lgkmcnt(12)
	v_mfma_f32_32x32x16_bf16 v[18:33], v[236:239], v[216:219], v[18:33]
	ds_read_b64_tr_b16 v[236:237], v148 offset:19520
	ds_read_b64_tr_b16 v[238:239], v148 offset:21056
	s_waitcnt lgkmcnt(11)
	v_mfma_f32_32x32x16_bf16 v[2:17], v[240:243], v[216:219], v[2:17]
	ds_read_b64_tr_b16 v[240:241], v148 offset:22528
	ds_read_b64_tr_b16 v[242:243], v148 offset:24064
	v_pk_fma_f32 v[58:59], v[58:59], s[54:55], v[224:225] op_sel:[0,1,0] op_sel_hi:[1,1,0] neg_lo:[0,0,1] neg_hi:[0,0,1]
	v_pk_fma_f32 v[60:61], v[60:61], s[54:55], v[224:225] op_sel:[0,1,0] op_sel_hi:[1,1,0] neg_lo:[0,0,1] neg_hi:[0,0,1]
	v_pk_fma_f32 v[62:63], v[62:63], s[54:55], v[224:225] op_sel:[0,1,0] op_sel_hi:[1,1,0] neg_lo:[0,0,1] neg_hi:[0,0,1]
	v_pk_fma_f32 v[64:65], v[64:65], s[54:55], v[224:225] op_sel:[0,1,0] op_sel_hi:[1,1,0] neg_lo:[0,0,1] neg_hi:[0,0,1]
	v_exp_f32_e32 v58, v58
	v_exp_f32_e32 v59, v59
	v_exp_f32_e32 v60, v60
	v_exp_f32_e32 v61, v61
	v_exp_f32_e32 v62, v62
	v_exp_f32_e32 v63, v63
	v_exp_f32_e32 v64, v64
	v_exp_f32_e32 v65, v65
	v_cvt_pk_bf16_f32 v220, v58, v59
	v_cvt_pk_bf16_f32 v221, v60, v61
	v_cvt_pk_bf16_f32 v222, v62, v63
	v_cvt_pk_bf16_f32 v223, v64, v65
	v_pk_add_f32 v[58:59], v[58:59], v[60:61]
	v_pk_add_f32 v[62:63], v[62:63], v[64:65]
	v_pk_add_f32 v[58:59], v[58:59], v[62:63]
	v_add_f32_e32 v58, v58, v59
	s_waitcnt lgkmcnt(10)
	v_mfma_f32_32x32x16_bf16 v[18:33], v[244:247], v[220:223], v[18:33]
	ds_read_b64_tr_b16 v[244:245], v148 offset:22592
	ds_read_b64_tr_b16 v[246:247], v148 offset:24128
	s_waitcnt lgkmcnt(9)
	v_mfma_f32_32x32x16_bf16 v[2:17], v[228:231], v[220:223], v[2:17]
	v_pk_fma_f32 v[34:35], v[34:35], s[54:55], v[224:225] op_sel:[0,1,0] op_sel_hi:[1,1,0] neg_lo:[0,0,1] neg_hi:[0,0,1]
	v_pk_fma_f32 v[36:37], v[36:37], s[54:55], v[224:225] op_sel:[0,1,0] op_sel_hi:[1,1,0] neg_lo:[0,0,1] neg_hi:[0,0,1]
	v_pk_fma_f32 v[38:39], v[38:39], s[54:55], v[224:225] op_sel:[0,1,0] op_sel_hi:[1,1,0] neg_lo:[0,0,1] neg_hi:[0,0,1]
	v_pk_fma_f32 v[40:41], v[40:41], s[54:55], v[224:225] op_sel:[0,1,0] op_sel_hi:[1,1,0] neg_lo:[0,0,1] neg_hi:[0,0,1]
	v_exp_f32_e32 v34, v34
	v_exp_f32_e32 v35, v35
	v_exp_f32_e32 v36, v36
	v_exp_f32_e32 v37, v37
	v_exp_f32_e32 v38, v38
	v_exp_f32_e32 v39, v39
	v_exp_f32_e32 v40, v40
	v_exp_f32_e32 v41, v41
	v_cvt_pk_bf16_f32 v216, v34, v35
	v_cvt_pk_bf16_f32 v217, v36, v37
	v_cvt_pk_bf16_f32 v218, v38, v39
	v_cvt_pk_bf16_f32 v219, v40, v41
	v_pk_add_f32 v[34:35], v[34:35], v[36:37]
	v_pk_add_f32 v[38:39], v[38:39], v[40:41]
	v_pk_add_f32 v[34:35], v[34:35], v[38:39]
	v_add_f32_e32 v34, v34, v35
	s_waitcnt lgkmcnt(6)
	v_mfma_f32_32x32x16_bf16 v[18:33], v[232:235], v[216:219], v[18:33]
	s_waitcnt lgkmcnt(4)
	v_mfma_f32_32x32x16_bf16 v[2:17], v[236:239], v[216:219], v[2:17]
	v_pk_fma_f32 v[42:43], v[42:43], s[54:55], v[224:225] op_sel:[0,1,0] op_sel_hi:[1,1,0] neg_lo:[0,0,1] neg_hi:[0,0,1]
	v_pk_fma_f32 v[44:45], v[44:45], s[54:55], v[224:225] op_sel:[0,1,0] op_sel_hi:[1,1,0] neg_lo:[0,0,1] neg_hi:[0,0,1]
	v_pk_fma_f32 v[46:47], v[46:47], s[54:55], v[224:225] op_sel:[0,1,0] op_sel_hi:[1,1,0] neg_lo:[0,0,1] neg_hi:[0,0,1]
	v_pk_fma_f32 v[48:49], v[48:49], s[54:55], v[224:225] op_sel:[0,1,0] op_sel_hi:[1,1,0] neg_lo:[0,0,1] neg_hi:[0,0,1]
	v_exp_f32_e32 v42, v42
	v_exp_f32_e32 v43, v43
	v_exp_f32_e32 v44, v44
	v_exp_f32_e32 v45, v45
	v_exp_f32_e32 v46, v46
	v_exp_f32_e32 v47, v47
	v_exp_f32_e32 v48, v48
	v_exp_f32_e32 v49, v49
	v_cvt_pk_bf16_f32 v220, v42, v43
	v_cvt_pk_bf16_f32 v221, v44, v45
	v_cvt_pk_bf16_f32 v222, v46, v47
	v_cvt_pk_bf16_f32 v223, v48, v49
	v_pk_add_f32 v[42:43], v[42:43], v[44:45]
	v_pk_add_f32 v[46:47], v[46:47], v[48:49]
	v_pk_add_f32 v[42:43], v[42:43], v[46:47]
	v_add_f32_e32 v42, v42, v43
	s_waitcnt lgkmcnt(2)
	v_mfma_f32_32x32x16_bf16 v[18:33], v[240:243], v[220:223], v[18:33]
	s_waitcnt lgkmcnt(0)
	v_mfma_f32_32x32x16_bf16 v[2:17], v[244:247], v[220:223], v[2:17]
	v_add_f32_e32 v50, v50, v58
	v_add_f32_e32 v34, v34, v42
	v_add_f32_e32 v50, v50, v34
	v_add_f32_e32 v154, v154, v50
	s_waitcnt lgkmcnt(0)
	s_barrier
	ds_read_b128 v[228:231], v150 offset:25600
	ds_read_b128 v[232:235], v150 offset:25632
	ds_read_b128 v[236:239], v150 offset:25664
	ds_read_b128 v[240:243], v150 offset:25696
	ds_read_b128 v[244:247], v150 offset:25728
	s_waitcnt lgkmcnt(4)
	v_mfma_f32_32x32x16_bf16 v[50:65], v[228:231], v[82:85], 0
	ds_read_b128 v[228:231], v150 offset:25760
	s_waitcnt lgkmcnt(4)
	v_mfma_f32_32x32x16_bf16 v[50:65], v[232:235], v[86:89], v[50:65]
	ds_read_b128 v[232:235], v150 offset:32256
	s_waitcnt lgkmcnt(4)
	v_mfma_f32_32x32x16_bf16 v[50:65], v[236:239], v[90:93], v[50:65]
	ds_read_b128 v[236:239], v150 offset:32288
	s_waitcnt lgkmcnt(4)
	v_mfma_f32_32x32x16_bf16 v[50:65], v[240:243], v[94:97], v[50:65]
	ds_read_b128 v[240:243], v150 offset:32320
	s_waitcnt lgkmcnt(4)
	v_mfma_f32_32x32x16_bf16 v[50:65], v[244:247], v[98:101], v[50:65]
	ds_read_b128 v[244:247], v150 offset:32352
	s_waitcnt lgkmcnt(4)
	v_mfma_f32_32x32x16_bf16 v[50:65], v[228:231], v[102:105], v[50:65]
	ds_read_b128 v[228:231], v150 offset:32384
	s_waitcnt lgkmcnt(4)
	v_mfma_f32_32x32x16_bf16 v[34:49], v[232:235], v[82:85], 0
	ds_read_b128 v[232:235], v150 offset:32416
	s_waitcnt lgkmcnt(4)
	v_mfma_f32_32x32x16_bf16 v[34:49], v[236:239], v[86:89], v[34:49]
	ds_read_b64_tr_b16 v[236:237], v148 offset:38912
	ds_read_b64_tr_b16 v[238:239], v148 offset:40448
	s_waitcnt lgkmcnt(5)
	v_mfma_f32_32x32x16_bf16 v[34:49], v[240:243], v[90:93], v[34:49]
	ds_read_b64_tr_b16 v[240:241], v148 offset:38976
	ds_read_b64_tr_b16 v[242:243], v148 offset:40512
	s_waitcnt lgkmcnt(6)
	v_mfma_f32_32x32x16_bf16 v[34:49], v[244:247], v[94:97], v[34:49]
	ds_read_b64_tr_b16 v[244:245], v148 offset:41984
	ds_read_b64_tr_b16 v[246:247], v148 offset:43520
	s_waitcnt lgkmcnt(7)
	v_mfma_f32_32x32x16_bf16 v[34:49], v[228:231], v[98:101], v[34:49]
	ds_read_b64_tr_b16 v[228:229], v148 offset:42048
	ds_read_b64_tr_b16 v[230:231], v148 offset:43584
	s_waitcnt lgkmcnt(8)
	v_mfma_f32_32x32x16_bf16 v[34:49], v[232:235], v[102:105], v[34:49]
	ds_read_b64_tr_b16 v[232:233], v148 offset:45056
	ds_read_b64_tr_b16 v[234:235], v148 offset:46592
	v_max3_f32 v224, s23, v50, v51
	v_max3_f32 v224, v224, v52, v53
	v_max3_f32 v224, v224, v54, v55
	v_max3_f32 v224, v224, v56, v57
	v_max3_f32 v224, v224, v58, v59
	v_max3_f32 v224, v224, v60, v61
	v_max3_f32 v224, v224, v62, v63
	v_max3_f32 v224, v224, v64, v65
	s_nop 1
	v_max3_f32 v225, s23, v34, v35
	v_max3_f32 v225, v225, v36, v37
	v_max3_f32 v225, v225, v38, v39
	v_max3_f32 v225, v225, v40, v41
	v_max3_f32 v225, v225, v42, v43
	v_max3_f32 v225, v225, v44, v45
	v_max3_f32 v225, v225, v46, v47
	v_max3_f32 v225, v225, v48, v49
	v_max_f32_e32 v224, v224, v225
	v_mov_b32_e32 v225, v224
	s_nop 1
	v_permlane32_swap_b32_e32 v224, v225
	v_max_f32_e32 v224, v224, v225
	v_mul_f32_e32 v224, s55, v224
	v_max_f32_e32 v213, v214, v224
	v_sub_f32_e32 v226, v214, v213
	v_exp_f32_e32 v226, v226
	v_mov_b32_e32 v224, v213
	v_pk_fma_f32 v[50:51], v[50:51], s[54:55], v[224:225] op_sel:[0,1,0] op_sel_hi:[1,1,0] neg_lo:[0,0,1] neg_hi:[0,0,1]
	v_pk_fma_f32 v[52:53], v[52:53], s[54:55], v[224:225] op_sel:[0,1,0] op_sel_hi:[1,1,0] neg_lo:[0,0,1] neg_hi:[0,0,1]
	v_pk_fma_f32 v[54:55], v[54:55], s[54:55], v[224:225] op_sel:[0,1,0] op_sel_hi:[1,1,0] neg_lo:[0,0,1] neg_hi:[0,0,1]
	v_pk_fma_f32 v[56:57], v[56:57], s[54:55], v[224:225] op_sel:[0,1,0] op_sel_hi:[1,1,0] neg_lo:[0,0,1] neg_hi:[0,0,1]
	v_exp_f32_e32 v50, v50
	v_exp_f32_e32 v51, v51
	v_exp_f32_e32 v52, v52
	v_exp_f32_e32 v53, v53
	v_exp_f32_e32 v54, v54
	v_exp_f32_e32 v55, v55
	v_exp_f32_e32 v56, v56
	v_exp_f32_e32 v57, v57
	v_mul_f32_e32 v154, v154, v226
	v_pk_mul_f32 v[18:19], v[18:19], v[226:227] op_sel_hi:[1,0]
	v_pk_mul_f32 v[20:21], v[20:21], v[226:227] op_sel_hi:[1,0]
	v_pk_mul_f32 v[22:23], v[22:23], v[226:227] op_sel_hi:[1,0]
	v_pk_mul_f32 v[24:25], v[24:25], v[226:227] op_sel_hi:[1,0]
	v_pk_mul_f32 v[26:27], v[26:27], v[226:227] op_sel_hi:[1,0]
	v_pk_mul_f32 v[28:29], v[28:29], v[226:227] op_sel_hi:[1,0]
	v_pk_mul_f32 v[30:31], v[30:31], v[226:227] op_sel_hi:[1,0]
	v_pk_mul_f32 v[32:33], v[32:33], v[226:227] op_sel_hi:[1,0]
	v_pk_mul_f32 v[2:3], v[2:3], v[226:227] op_sel_hi:[1,0]
	v_pk_mul_f32 v[4:5], v[4:5], v[226:227] op_sel_hi:[1,0]
	v_pk_mul_f32 v[6:7], v[6:7], v[226:227] op_sel_hi:[1,0]
	v_pk_mul_f32 v[8:9], v[8:9], v[226:227] op_sel_hi:[1,0]
	v_pk_mul_f32 v[10:11], v[10:11], v[226:227] op_sel_hi:[1,0]
	v_pk_mul_f32 v[12:13], v[12:13], v[226:227] op_sel_hi:[1,0]
	v_pk_mul_f32 v[14:15], v[14:15], v[226:227] op_sel_hi:[1,0]
	v_pk_mul_f32 v[16:17], v[16:17], v[226:227] op_sel_hi:[1,0]
	v_cvt_pk_bf16_f32 v216, v50, v51
	v_cvt_pk_bf16_f32 v217, v52, v53
	v_cvt_pk_bf16_f32 v218, v54, v55
	v_cvt_pk_bf16_f32 v219, v56, v57
	v_pk_add_f32 v[50:51], v[50:51], v[52:53]
	v_pk_add_f32 v[54:55], v[54:55], v[56:57]
	v_pk_add_f32 v[50:51], v[50:51], v[54:55]
	v_add_f32_e32 v50, v50, v51
	s_waitcnt lgkmcnt(8)
	v_mfma_f32_32x32x16_bf16 v[18:33], v[236:239], v[216:219], v[18:33]
	ds_read_b64_tr_b16 v[236:237], v148 offset:45120
	ds_read_b64_tr_b16 v[238:239], v148 offset:46656
	s_waitcnt lgkmcnt(8)
	v_mfma_f32_32x32x16_bf16 v[2:17], v[240:243], v[216:219], v[2:17]
	ds_read_b64_tr_b16 v[240:241], v148 offset:48128
	ds_read_b64_tr_b16 v[242:243], v148 offset:49664
	v_pk_fma_f32 v[58:59], v[58:59], s[54:55], v[224:225] op_sel:[0,1,0] op_sel_hi:[1,1,0] neg_lo:[0,0,1] neg_hi:[0,0,1]
	v_pk_fma_f32 v[60:61], v[60:61], s[54:55], v[224:225] op_sel:[0,1,0] op_sel_hi:[1,1,0] neg_lo:[0,0,1] neg_hi:[0,0,1]
	v_pk_fma_f32 v[62:63], v[62:63], s[54:55], v[224:225] op_sel:[0,1,0] op_sel_hi:[1,1,0] neg_lo:[0,0,1] neg_hi:[0,0,1]
	v_pk_fma_f32 v[64:65], v[64:65], s[54:55], v[224:225] op_sel:[0,1,0] op_sel_hi:[1,1,0] neg_lo:[0,0,1] neg_hi:[0,0,1]
	v_exp_f32_e32 v58, v58
	v_exp_f32_e32 v59, v59
	v_exp_f32_e32 v60, v60
	v_exp_f32_e32 v61, v61
	v_exp_f32_e32 v62, v62
	v_exp_f32_e32 v63, v63
	v_exp_f32_e32 v64, v64
	v_exp_f32_e32 v65, v65
	v_cvt_pk_bf16_f32 v220, v58, v59
	v_cvt_pk_bf16_f32 v221, v60, v61
	v_cvt_pk_bf16_f32 v222, v62, v63
	v_cvt_pk_bf16_f32 v223, v64, v65
	v_pk_add_f32 v[58:59], v[58:59], v[60:61]
	v_pk_add_f32 v[62:63], v[62:63], v[64:65]
	v_pk_add_f32 v[58:59], v[58:59], v[62:63]
	v_add_f32_e32 v58, v58, v59
	s_waitcnt lgkmcnt(8)
	v_mfma_f32_32x32x16_bf16 v[18:33], v[244:247], v[220:223], v[18:33]
	ds_read_b64_tr_b16 v[244:245], v148 offset:48192
	ds_read_b64_tr_b16 v[246:247], v148 offset:49728
	s_waitcnt lgkmcnt(8)
	v_mfma_f32_32x32x16_bf16 v[2:17], v[228:231], v[220:223], v[2:17]
	v_pk_fma_f32 v[34:35], v[34:35], s[54:55], v[224:225] op_sel:[0,1,0] op_sel_hi:[1,1,0] neg_lo:[0,0,1] neg_hi:[0,0,1]
	v_pk_fma_f32 v[36:37], v[36:37], s[54:55], v[224:225] op_sel:[0,1,0] op_sel_hi:[1,1,0] neg_lo:[0,0,1] neg_hi:[0,0,1]
	v_pk_fma_f32 v[38:39], v[38:39], s[54:55], v[224:225] op_sel:[0,1,0] op_sel_hi:[1,1,0] neg_lo:[0,0,1] neg_hi:[0,0,1]
	v_pk_fma_f32 v[40:41], v[40:41], s[54:55], v[224:225] op_sel:[0,1,0] op_sel_hi:[1,1,0] neg_lo:[0,0,1] neg_hi:[0,0,1]
	v_exp_f32_e32 v34, v34
	v_exp_f32_e32 v35, v35
	v_exp_f32_e32 v36, v36
	v_exp_f32_e32 v37, v37
	v_exp_f32_e32 v38, v38
	v_exp_f32_e32 v39, v39
	v_exp_f32_e32 v40, v40
	v_exp_f32_e32 v41, v41
	v_cvt_pk_bf16_f32 v216, v34, v35
	v_cvt_pk_bf16_f32 v217, v36, v37
	v_cvt_pk_bf16_f32 v218, v38, v39
	v_cvt_pk_bf16_f32 v219, v40, v41
	v_pk_add_f32 v[34:35], v[34:35], v[36:37]
	v_pk_add_f32 v[38:39], v[38:39], v[40:41]
	v_pk_add_f32 v[34:35], v[34:35], v[38:39]
	v_add_f32_e32 v34, v34, v35
	s_waitcnt lgkmcnt(6)
	v_mfma_f32_32x32x16_bf16 v[18:33], v[232:235], v[216:219], v[18:33]
	s_waitcnt lgkmcnt(4)
	v_mfma_f32_32x32x16_bf16 v[2:17], v[236:239], v[216:219], v[2:17]
	v_pk_fma_f32 v[42:43], v[42:43], s[54:55], v[224:225] op_sel:[0,1,0] op_sel_hi:[1,1,0] neg_lo:[0,0,1] neg_hi:[0,0,1]
	v_pk_fma_f32 v[44:45], v[44:45], s[54:55], v[224:225] op_sel:[0,1,0] op_sel_hi:[1,1,0] neg_lo:[0,0,1] neg_hi:[0,0,1]
	v_pk_fma_f32 v[46:47], v[46:47], s[54:55], v[224:225] op_sel:[0,1,0] op_sel_hi:[1,1,0] neg_lo:[0,0,1] neg_hi:[0,0,1]
	v_pk_fma_f32 v[48:49], v[48:49], s[54:55], v[224:225] op_sel:[0,1,0] op_sel_hi:[1,1,0] neg_lo:[0,0,1] neg_hi:[0,0,1]
	v_exp_f32_e32 v42, v42
	v_exp_f32_e32 v43, v43
	v_exp_f32_e32 v44, v44
	v_exp_f32_e32 v45, v45
	v_exp_f32_e32 v46, v46
	v_exp_f32_e32 v47, v47
	v_exp_f32_e32 v48, v48
	v_exp_f32_e32 v49, v49
	v_cvt_pk_bf16_f32 v220, v42, v43
	v_cvt_pk_bf16_f32 v221, v44, v45
	v_cvt_pk_bf16_f32 v222, v46, v47
	v_cvt_pk_bf16_f32 v223, v48, v49
	v_pk_add_f32 v[42:43], v[42:43], v[44:45]
	v_pk_add_f32 v[46:47], v[46:47], v[48:49]
	v_pk_add_f32 v[42:43], v[42:43], v[46:47]
	v_add_f32_e32 v42, v42, v43
	s_waitcnt lgkmcnt(2)
	v_mfma_f32_32x32x16_bf16 v[18:33], v[240:243], v[220:223], v[18:33]
	s_waitcnt lgkmcnt(0)
	v_mfma_f32_32x32x16_bf16 v[2:17], v[244:247], v[220:223], v[2:17]
	v_add_f32_e32 v50, v50, v58
	v_add_f32_e32 v34, v34, v42
	v_add_f32_e32 v50, v50, v34
	v_add_f32_e32 v154, v154, v50
	s_waitcnt lgkmcnt(0)
	s_barrier
